# ffn-norm row loop: the eight norm-weight loads hoisted out of the row loop (done once into spare registers); per-row vmcnt(0) waits behind write-through stores replaced by one counted wait
# speedup vs baseline: 1.0044x; 1.0044x over previous
; template <int MODE> __device__ __forceinline__ void norm_phase(const Ptrs& P, const float* nw, int gw, int NGW, int lane) {
;     ...
;     const int nrows = (MODE == 2) ? MMAIN : MTOK;
;     f32x4 xn[8]; u32x2 hn[8];
;     ...
;     int row = gw;
;     if (row < nrows) NORM_LOAD(row);
;     for (; row < nrows; row += NGW) {
;         f32x4 v[8]; float ss = 0.f;
; #pragma unroll
;         for (int j = 0; j < 8; ++j) v[j] = (MODE == 1) ? xn[j] : (f32x4){bflo(hn[j].x), bfhi(hn[j].x), bflo(hn[j].y), bfhi(hn[j].y)};
;         if (row + NGW < nrows) NORM_LOAD(row + NGW);
; #pragma unroll
;         for (int j = 0; j < 8; ++j) ss += (v[j][0] * v[j][0] + v[j][1] * v[j][1]) + (v[j][2] * v[j][2] + v[j][3] * v[j][3]);
;         ss = wave_sum(ss, lane);
;         const float rstd = 1.0f / sqrtf(ss * (1.0f / DM) + EPS);
;     ...
;             const f32x4 w4 = ((const f32x4*)nw)[64 * j + lane];
.LBB0_1436:
	s_or_b64 exec, exec, s[4:5]
	s_waitcnt lgkmcnt(0)
	s_barrier
	s_getreg_b32 s3, hwreg(HW_REG_HW_ID, 0, 6)
	s_and_b32 s3, s3, 63
	s_lshl_b32 s3, s3, 2
	s_add_i32 s3, s3, 0
	s_add_i32 s3, s3, 0x27ef0
	v_mov_b32_e32 v0, s3
	ds_read_b32 v0, v0
	s_mov_b64 s[6:7], s[0:1]
	s_waitcnt lgkmcnt(0)
	v_readfirstlane_b32 s3, v0
	s_nop 1
	v_lshl_add_u32 v1, s3, 6, v213
	v_readlane_b32 s3, v255, 18
	v_ashrrev_i32_e32 v0, 6, v1
	s_nop 0
	v_add_u32_e32 v0, s3, v0
	s_mov_b32 s3, 0x8020
	v_cmp_gt_i32_e32 vcc, s3, v0
	s_and_saveexec_b64 s[4:5], vcc
	s_xor_b64 s[4:5], exec, s[4:5]
	s_cbranch_execz .LBB0_1442
	global_load_dwordx2 v[12:13], v16, s[6:7] offset:184
	global_load_dwordx2 v[2:3], v16, s[6:7] offset:128
	s_lshl_b32 s96, s82, 11
	v_and_b32_e32 v6, 63, v1
	v_ashrrev_i32_e32 v1, 31, v0
	s_lshl_b64 s[6:7], s[96:97], 2
	v_lshlrev_b64 v[14:15], 12, v[0:1]
	v_lshlrev_b32_e32 v18, 3, v6
	v_mov_b32_e32 v19, v16
	s_mov_b32 s3, 0x100000
	v_lshlrev_b32_e32 v20, 4, v6
	v_mov_b32_e32 v21, v16
	v_mov_b32_e32 v7, v16
	v_or_b32_e32 v8, 0x1800, v20
	v_mov_b32_e32 v9, v16
	s_movk_i32 s12, 0x781f
	s_mov_b32 s13, 0xf800000
	s_waitcnt vmcnt(0)
	v_lshl_add_u64 v[10:11], v[2:3], 0, s[6:7]
	v_lshl_add_u64 v[2:3], v[12:13], 0, v[14:15]
	v_lshl_add_u64 v[2:3], v[2:3], 0, v[18:19]
	s_mov_b64 s[6:7], 0x100000
	v_lshl_add_u64 v[4:5], v[2:3], 0, s[6:7]
	v_add_co_u32_e32 v2, vcc, s3, v2
	v_or_b32_e32 v14, v14, v18
	s_nop 0
	v_addc_co_u32_e32 v3, vcc, 0, v3, vcc
	global_load_dwordx2 v[46:47], v[2:3], off
	global_load_dwordx2 v[44:45], v[4:5], off offset:512
	global_load_dwordx2 v[40:41], v[4:5], off offset:1024
	global_load_dwordx2 v[38:39], v[4:5], off offset:1536
	global_load_dwordx2 v[32:33], v[4:5], off offset:2048
	global_load_dwordx2 v[36:37], v[4:5], off offset:2560
	global_load_dwordx2 v[34:35], v[4:5], off offset:3072
	global_load_dwordx2 v[42:43], v[4:5], off offset:3584
	v_lshlrev_b32_e32 v2, 2, v6
	v_xor_b32_e32 v1, 4, v2
	v_xor_b32_e32 v17, 8, v2
	v_xor_b32_e32 v54, 16, v2
	v_xor_b32_e32 v55, 32, v2
	v_xor_b32_e32 v56, 64, v2
	v_xor_b32_e32 v57, 0x80, v2
	v_lshl_add_u64 v[2:3], v[10:11], 0, v[20:21]
	v_or_b32_e32 v4, 0x1000, v20
	v_mov_b32_e32 v5, v16
	v_or_b32_e32 v6, 0x1400, v20
	v_or_b32_e32 v20, 0x1c00, v20
	v_lshl_add_u64 v[12:13], v[12:13], 0, v[14:15]
	s_mov_b64 s[6:7], 0x10300000
	v_lshl_add_u64 v[4:5], v[10:11], 0, v[4:5]
	v_lshl_add_u64 v[6:7], v[10:11], 0, v[6:7]
	v_lshl_add_u64 v[8:9], v[10:11], 0, v[8:9]
	v_lshl_add_u64 v[10:11], v[10:11], 0, v[20:21]
	v_lshl_add_u64 v[12:13], v[12:13], 0, s[6:7]
	s_mov_b64 s[6:7], 0
	s_movk_i32 s3, 0x7820
	s_waitcnt vmcnt(7)
	v_mov_b64_e32 v[30:31], v[46:47]
	s_waitcnt vmcnt(6)
	v_mov_b64_e32 v[28:29], v[44:45]
	s_waitcnt vmcnt(5)
	v_mov_b64_e32 v[26:27], v[40:41]
	s_waitcnt vmcnt(4)
	v_mov_b64_e32 v[24:25], v[38:39]
	s_waitcnt vmcnt(3)
	v_mov_b64_e32 v[22:23], v[32:33]
	s_waitcnt vmcnt(2)
	v_mov_b64_e32 v[20:21], v[36:37]
	s_waitcnt vmcnt(1)
	v_mov_b64_e32 v[18:19], v[34:35]
	s_waitcnt vmcnt(0)
	v_mov_b64_e32 v[14:15], v[42:43]
	global_load_dwordx4 v[132:135], v[2:3], off
	global_load_dwordx4 v[136:139], v[2:3], off offset:1024
	global_load_dwordx4 v[140:143], v[2:3], off offset:2048
	global_load_dwordx4 v[144:147], v[2:3], off offset:3072
	global_load_dwordx4 v[148:151], v[4:5], off
	global_load_dwordx4 v[152:155], v[6:7], off
	global_load_dwordx4 v[156:159], v[8:9], off
	global_load_dwordx4 v[160:163], v[10:11], off
	s_waitcnt vmcnt(0)
	s_branch .LBB0_1439
.LBB0_1438:
	s_or_b64 exec, exec, s[8:9]
	v_and_b32_e32 v65, 0xffff0000, v46
	v_and_b32_e32 v64, 0xffff0000, v44
	v_and_b32_e32 v69, 0xffff0000, v47
	v_and_b32_e32 v68, 0xffff0000, v45
	v_lshlrev_b32_e32 v63, 16, v46
	v_lshlrev_b32_e32 v62, 16, v44
	v_lshlrev_b32_e32 v67, 16, v47
	v_lshlrev_b32_e32 v66, 16, v45
	v_lshlrev_b32_e32 v71, 16, v41
	v_lshlrev_b32_e32 v70, 16, v40
	v_and_b32_e32 v73, 0xffff0000, v41
	v_and_b32_e32 v72, 0xffff0000, v40
	v_lshlrev_b32_e32 v50, 16, v38
	v_and_b32_e32 v51, 0xffff0000, v38
	v_lshlrev_b32_e32 v38, 16, v42
	v_and_b32_e32 v79, 0xffff0000, v42
	v_lshlrev_b32_e32 v40, 16, v43
	v_and_b32_e32 v41, 0xffff0000, v43
	v_pk_mul_f32 v[42:43], v[64:65], v[64:65]
	v_pk_mul_f32 v[58:59], v[68:69], v[68:69]
	v_pk_fma_f32 v[42:43], v[62:63], v[62:63], v[42:43]
	v_pk_fma_f32 v[58:59], v[66:67], v[66:67], v[58:59]
	v_lshlrev_b32_e32 v52, 16, v39
	v_pk_add_f32 v[42:43], v[42:43], v[58:59]
	v_lshlrev_b32_e32 v46, 16, v32
	v_pk_add_f32 v[42:43], v[42:43], v[42:43] op_sel_hi:[0,1]
	v_pk_mul_f32 v[58:59], v[72:73], v[72:73]
	v_and_b32_e32 v53, 0xffff0000, v39
	v_pk_fma_f32 v[58:59], v[70:71], v[70:71], v[58:59]
	v_mul_f32_e32 v47, v50, v50
	v_mul_f32_e32 v61, v51, v51
	v_mul_f32_e32 v42, v52, v52
	v_mov_b32_e32 v60, v46
	v_and_b32_e32 v78, 0xffff0000, v32
	v_lshlrev_b32_e32 v48, 16, v33
	v_and_b32_e32 v49, 0xffff0000, v33
	v_pk_add_f32 v[58:59], v[58:59], v[58:59] op_sel_hi:[0,1]
	v_pk_fma_f32 v[74:75], v[52:53], v[52:53], v[42:43] op_sel_hi:[1,1,0]
	v_pk_add_f32 v[60:61], v[46:47], v[60:61]
	v_mul_f32_e32 v74, v78, v78
	v_mul_f32_e32 v58, v48, v48
	v_mul_f32_e32 v42, v49, v49
	v_mul_f32_e32 v76, v46, v46
	v_mov_b32_e32 v77, v61
	v_pk_add_f32 v[60:61], v[76:77], v[74:75]
	v_pk_add_f32 v[42:43], v[58:59], v[42:43]
	v_lshlrev_b32_e32 v45, 16, v37
	v_lshlrev_b32_e32 v44, 16, v36
	v_and_b32_e32 v37, 0xffff0000, v37
	v_and_b32_e32 v36, 0xffff0000, v36
	v_pk_add_f32 v[42:43], v[60:61], v[42:43]
	v_lshlrev_b32_e32 v32, 16, v34
	v_and_b32_e32 v33, 0xffff0000, v34
	v_lshlrev_b32_e32 v34, 16, v35
	v_pk_add_f32 v[42:43], v[42:43], v[42:43] op_sel_hi:[0,1]
	v_pk_mul_f32 v[58:59], v[36:37], v[36:37]
	v_and_b32_e32 v35, 0xffff0000, v35
	v_pk_fma_f32 v[58:59], v[44:45], v[44:45], v[58:59]
	v_mul_f32_e32 v39, v32, v32
	v_mul_f32_e32 v61, v33, v33
	v_mul_f32_e32 v42, v34, v34
	v_mov_b32_e32 v60, v38
	v_pk_add_f32 v[58:59], v[58:59], v[58:59] op_sel_hi:[0,1]
	v_pk_fma_f32 v[74:75], v[34:35], v[34:35], v[42:43] op_sel_hi:[1,1,0]
	v_pk_add_f32 v[60:61], v[38:39], v[60:61]
	v_mul_f32_e32 v74, v79, v79
	v_mul_f32_e32 v58, v40, v40
	v_mul_f32_e32 v42, v41, v41
	v_mul_f32_e32 v76, v38, v38
	v_mov_b32_e32 v77, v61
	v_pk_add_f32 v[60:61], v[76:77], v[74:75]
	v_pk_add_f32 v[42:43], v[58:59], v[42:43]
	v_mov_b32_e32 v76, v67
	v_pk_add_f32 v[42:43], v[60:61], v[42:43]
	v_add_f32_e32 v39, v42, v43
	ds_bpermute_b32 v42, v1, v39
	v_mov_b32_e32 v77, v69
	v_mov_b32_e32 v67, v68
	v_add_u32_e32 v0, 0x800, v0
	s_waitcnt lgkmcnt(0)
; __device__ __forceinline__ void store8_wt(void* p, u32x2w v) { asm volatile("global_store_dwordx2 %0, %1, off sc1\n\ts_nop 1" :: "v"(p), "v"(v) : "memory"); }
; __device__ __forceinline__ unsigned pk2(float lo, float hi) { f32x2_t v = {lo, hi}; bf16x2_t b = __builtin_convertvector(v, bf16x2_t); return __builtin_bit_cast(unsigned, b); }
; template <int MODE> __device__ __forceinline__ void norm_phase(const Ptrs& P, const float* nw, int gw, int NGW, int lane) {
;     ...
;         ss = wave_sum(ss, lane);
;         const float rstd = 1.0f / sqrtf(ss * (1.0f / DM) + EPS);
;         if (MODE == 1) {
; #pragma unroll
;             for (int j = 0; j < 8; ++j) { u32x2 w; w.x = pk2(v[j][0], v[j][1]); w.y = pk2(v[j][2], v[j][3]); pg8::store8_wt((u32x2*)(H + (size_t)row * DM) + 64 * j + lane, w); }
;         }
; #pragma unroll
;         for (int j = 0; j < 8; ++j) {
;             const f32x4 w4 = ((const f32x4*)nw)[64 * j + lane];
;             const f32x4 o = v[j] * rstd * w4;
;             if (MODE == 2) ((f32x4*)(P.out + (size_t)row * DM))[64 * j + lane] = o;
;             else { u32x2 w; w.x = pk2(o[0], o[1]); w.y = pk2(o[2], o[3]); pg8::store8_wt((u32x2*)(U + (size_t)row * DM) + 64 * j + lane, w); }
;         }
	v_add_f32_e32 v39, v39, v42
	ds_bpermute_b32 v42, v17, v39
	s_waitcnt lgkmcnt(0)
	v_add_f32_e32 v39, v39, v42
	ds_bpermute_b32 v42, v54, v39
	s_waitcnt lgkmcnt(0)
	v_add_f32_e32 v39, v39, v42
	ds_bpermute_b32 v42, v55, v39
	s_waitcnt lgkmcnt(0)
	v_add_f32_e32 v39, v39, v42
	ds_bpermute_b32 v42, v56, v39
	s_waitcnt lgkmcnt(0)
	v_add_f32_e32 v39, v39, v42
	ds_bpermute_b32 v42, v57, v39
	s_waitcnt lgkmcnt(0)
	v_add_f32_e32 v39, v39, v42
	v_fmamk_f32 v39, v39, 0x3a000000, v234
	v_mul_f32_e32 v42, 0x4f800000, v39
	v_cmp_gt_f32_e32 vcc, s13, v39
	s_nop 1
	v_cndmask_b32_e32 v39, v39, v42, vcc
	v_sqrt_f32_e32 v42, v39
	s_nop 0
	v_add_u32_e32 v43, -1, v42
	v_fma_f32 v47, -v43, v42, v39
	v_cmp_ge_f32_e64 s[38:39], 0, v47
	v_add_u32_e32 v47, 1, v42
	s_nop 0
	v_cndmask_b32_e64 v43, v42, v43, s[38:39]
	v_fma_f32 v42, -v47, v42, v39
	v_cmp_lt_f32_e64 s[38:39], 0, v42
	s_nop 1
	v_cndmask_b32_e64 v42, v43, v47, s[38:39]
	v_mul_f32_e32 v43, 0x37800000, v42
	v_cndmask_b32_e32 v42, v42, v43, vcc
	v_cmp_class_f32_e32 vcc, v39, v235
	s_nop 1
	v_cndmask_b32_e32 v39, v42, v39, vcc
	v_div_scale_f32 v42, s[8:9], v39, v39, 1.0
	v_rcp_f32_e32 v43, v42
	s_mov_b64 s[8:9], 0x200
	v_fma_f32 v47, -v42, v43, 1.0
	v_fmac_f32_e32 v43, v47, v43
	v_div_scale_f32 v47, vcc, 1.0, v39, 1.0
	v_mul_f32_e32 v74, v47, v43
	v_fma_f32 v75, -v42, v74, v47
	v_fmac_f32_e32 v74, v75, v43
	v_fma_f32 v42, -v42, v74, v47
	v_div_fmas_f32 v42, v42, v43, v74
	v_div_fixup_f32 v74, v42, v39, 1.0
	v_mov_b32_e32 v42, v63
	v_mov_b32_e32 v43, v65
	v_pk_mul_f32 v[42:43], v[42:43], v[74:75] op_sel_hi:[1,0]
	v_pk_mul_f32 v[76:77], v[76:77], v[74:75] op_sel_hi:[1,0]
	v_pk_mul_f32 v[42:43], v[132:133], v[42:43]
	v_pk_mul_f32 v[60:61], v[134:135], v[76:77]
	v_cvt_pk_bf16_f32 v42, v42, v43
	v_cvt_pk_bf16_f32 v43, v60, v61
	global_store_dwordx2 v[12:13], v[42:43], off sc1
	s_nop 1
	v_mov_b32_e32 v63, v64
	v_pk_mul_f32 v[62:63], v[62:63], v[74:75] op_sel_hi:[1,0]
	v_pk_mul_f32 v[64:65], v[66:67], v[74:75] op_sel_hi:[1,0]
	v_lshl_add_u64 v[42:43], v[12:13], 0, s[8:9]
	s_mov_b64 s[8:9], 0x400
	v_pk_mul_f32 v[50:51], v[50:51], v[74:75] op_sel_hi:[1,0]
	v_pk_mul_f32 v[52:53], v[52:53], v[74:75] op_sel_hi:[1,0]
	v_mov_b32_e32 v47, v78
	v_pk_mul_f32 v[46:47], v[46:47], v[74:75] op_sel_hi:[1,0]
	v_pk_mul_f32 v[48:49], v[48:49], v[74:75] op_sel_hi:[1,0]
	v_pk_mul_f32 v[32:33], v[32:33], v[74:75] op_sel_hi:[1,0]
	v_pk_mul_f32 v[34:35], v[34:35], v[74:75] op_sel_hi:[1,0]
	v_mov_b32_e32 v39, v79
	v_pk_mul_f32 v[38:39], v[38:39], v[74:75] op_sel_hi:[1,0]
	v_pk_mul_f32 v[40:41], v[40:41], v[74:75] op_sel_hi:[1,0]
	v_pk_mul_f32 v[60:61], v[138:139], v[64:65]
	v_pk_mul_f32 v[58:59], v[136:137], v[62:63]
	v_mov_b32_e32 v62, v70
	v_cvt_pk_bf16_f32 v58, v58, v59
	v_cvt_pk_bf16_f32 v59, v60, v61
	global_store_dwordx2 v[42:43], v[58:59], off sc1
	s_nop 1
	v_mov_b32_e32 v63, v72
	v_mov_b32_e32 v72, v71
	v_pk_mul_f32 v[62:63], v[74:75], v[62:63] op_sel_hi:[0,1]
	v_pk_mul_f32 v[64:65], v[74:75], v[72:73] op_sel_hi:[0,1]
	v_lshl_add_u64 v[42:43], v[12:13], 0, s[8:9]
	s_mov_b64 s[8:9], 0x600
	v_pk_mul_f32 v[60:61], v[142:143], v[64:65]
	v_pk_mul_f32 v[58:59], v[140:141], v[62:63]
	s_nop 0
	v_cvt_pk_bf16_f32 v58, v58, v59
	v_cvt_pk_bf16_f32 v59, v60, v61
	global_store_dwordx2 v[42:43], v[58:59], off sc1
	s_nop 1
	v_lshl_add_u64 v[42:43], v[12:13], 0, s[8:9]
	s_mov_b64 s[8:9], 0x800
	v_pk_mul_f32 v[52:53], v[146:147], v[52:53]
	v_pk_mul_f32 v[50:51], v[144:145], v[50:51]
	s_nop 0
	v_cvt_pk_bf16_f32 v50, v50, v51
	v_cvt_pk_bf16_f32 v51, v52, v53
	global_store_dwordx2 v[42:43], v[50:51], off sc1
	s_nop 1
	v_lshl_add_u64 v[42:43], v[12:13], 0, s[8:9]
	s_mov_b64 s[8:9], 0xa00
	v_pk_mul_f32 v[48:49], v[48:49], v[150:151]
	v_pk_mul_f32 v[46:47], v[46:47], v[148:149]
	v_mov_b32_e32 v50, v44
	v_cvt_pk_bf16_f32 v46, v46, v47
	v_cvt_pk_bf16_f32 v47, v48, v49
	global_store_dwordx2 v[42:43], v[46:47], off sc1
	s_nop 1
	v_mov_b32_e32 v51, v36
	v_mov_b32_e32 v36, v45
	v_pk_mul_f32 v[44:45], v[74:75], v[50:51] op_sel_hi:[0,1]
	v_pk_mul_f32 v[36:37], v[74:75], v[36:37] op_sel_hi:[0,1]
	v_lshl_add_u64 v[42:43], v[12:13], 0, s[8:9]
	s_mov_b64 s[8:9], 0xc00
	v_pk_mul_f32 v[36:37], v[36:37], v[154:155]
	v_pk_mul_f32 v[44:45], v[44:45], v[152:153]
	s_nop 0
	v_cvt_pk_bf16_f32 v44, v44, v45
	v_cvt_pk_bf16_f32 v45, v36, v37
	global_store_dwordx2 v[42:43], v[44:45], off sc1
	s_nop 1
	v_lshl_add_u64 v[36:37], v[12:13], 0, s[8:9]
	s_mov_b64 s[8:9], 0xe00
	v_lshl_add_u64 v[48:49], v[12:13], 0, s[8:9]
	s_mov_b64 s[8:9], 0x800000
	v_lshl_add_u64 v[12:13], v[12:13], 0, s[8:9]
	v_pk_mul_f32 v[34:35], v[34:35], v[158:159]
	v_pk_mul_f32 v[32:33], v[32:33], v[156:157]
	s_waitcnt vmcnt(6)
	v_mov_b64_e32 v[42:43], v[14:15]
	v_cvt_pk_bf16_f32 v32, v32, v33
	v_cvt_pk_bf16_f32 v33, v34, v35
	global_store_dwordx2 v[36:37], v[32:33], off sc1
	s_nop 1
	v_mov_b64_e32 v[34:35], v[18:19]
	v_mov_b64_e32 v[36:37], v[20:21]
	v_mov_b64_e32 v[32:33], v[22:23]
	v_pk_mul_f32 v[40:41], v[40:41], v[162:163]
	v_pk_mul_f32 v[38:39], v[38:39], v[160:161]
	v_mov_b64_e32 v[44:45], v[28:29]
	v_cvt_pk_bf16_f32 v38, v38, v39
	v_cvt_pk_bf16_f32 v39, v40, v41
	global_store_dwordx2 v[48:49], v[38:39], off sc1
	s_nop 1
	v_mov_b64_e32 v[38:39], v[24:25]
	v_mov_b64_e32 v[40:41], v[26:27]
	v_mov_b64_e32 v[46:47], v[30:31]
	s_andn2_b64 exec, exec, s[6:7]
	s_cbranch_execz .LBB0_1441
